# in-proj -> attention seam: workgroups arrive after 5 GEMM rounds (tiles mixer A needs) and run their last GEMM unit(s) before waiting; mixer B waits once per workgroup on a second counter
# speedup vs baseline: 1.0340x; 1.0074x over previous
; __global__ void __launch_bounds__(NWAVES * 64, 2) mega_fwd(Args a) {
;     ...
;         for (int part = 0; part < 2; ++part) {
;             pg8::RangeOrder R{S, 0, 1 << 30};
;             if (split7) { if (part == 0) { R.lo = 0; R.hi = 6; } else { R.lo = 6; R.hi = 7; } } else if (part == 1) break;
;             if (part == 1 && bx >= 64) break;
.LBB0_68:
	s_andn2_b64 vcc, exec, s[20:21]
	s_cbranch_vccnz .LBB0_70
	s_and_b64 s[4:5], s[10:11], exec
	s_cselect_b32 s100, 6, 7
	s_and_b64 s[4:5], s[16:17], exec
	s_cselect_b32 s55, 0, 5
	s_cselect_b32 s56, 5, s100
	s_mov_b64 s[4:5], -1
	s_branch .LBB0_71

; #define LAS __attribute__((address_space(3)))
;     __host__ __device__ bool next(int i, Unit& u) const {
;         const long L = (long)i * G + c; if (L >= nwg) return false;
;         int wgid = (int)L; { const int q = nwg / NXCD, r = nwg % NXCD, xcd = wgid % NXCD, off = wgid / NXCD; wgid = (xcd < r ? xcd * (q + 1) : r * (q + 1) + (xcd - r) * q) + off; }
;         const int nig = WGM * nN, gid = wgid / nig, fm = gid * WGM, gsz = (nM - fm) < WGM ? (nM - fm) : WGM;
;         u.pm = fm + ((wgid % nig) % gsz); u.pn = (wgid % nig) / gsz; return true;
; __global__ void __launch_bounds__(NWAVES * 64, 2) mega_fwd(Args a) {
;     ...
;             if (part == 1 && bx >= 64) break;
;             pg8::gemm_phase<pg8::EpiInProj, pg8::RangeOrder, true, true>((LAS unsigned char*)lds, g, R, E);
.LBB0_71:
	s_mov_b64 s[4:5], 0
	s_andn2_b64 vcc, exec, s[4:5]
	s_mov_b64 s[4:5], -1
	s_cbranch_vccz .LBB0_65
	v_readfirstlane_b32 s12, v229
	s_cmp_ge_u32 s55, s56
	s_mov_b64 s[18:19], 0
	s_cbranch_scc1 .LBB0_75
	s_mul_i32 s5, s55, s83
	s_mul_hi_i32 s4, s55, s83
	s_add_u32 s20, s5, s82
	s_addc_u32 s21, s4, s50
	v_cmp_gt_i64_e32 vcc, s[20:21], v[162:163]
	s_cbranch_vccnz .LBB0_75
	s_ashr_i32 s4, s20, 31
	s_lshr_b32 s4, s4, 29
	s_add_i32 s4, s20, s4
	s_ashr_i32 s5, s4, 3
	s_and_b32 s4, s4, -8
	s_sub_i32 s4, s20, s4
	s_cmp_lt_i32 s4, 0
	s_cselect_b32 s18, s51, 0xc8
	s_mul_i32 s4, s4, s18
	s_add_i32 s4, s4, s5
	s_mul_hi_i32 s5, s4, 0x51eb851f
	s_lshr_b32 s18, s5, 31
	s_ashr_i32 s5, s5, 6
	s_add_i32 s5, s5, s18
	s_lshl_b32 s18, s5, 3
	s_sub_i32 s19, 64, s18
	s_min_i32 s19, s19, 8
	s_abs_i32 s20, s19
	v_cvt_f32_u32_e32 v0, s20
	s_sub_i32 s22, 0, s20
	s_mulk_i32 s5, 0xc8
	s_sub_i32 s4, s4, s5
	v_rcp_iflag_f32_e32 v0, v0
	s_abs_i32 s5, s4
	s_xor_b32 s21, s4, s19
	s_ashr_i32 s21, s21, 31
	v_mul_f32_e32 v0, 0x4f7ffffe, v0
	v_cvt_u32_f32_e32 v0, v0
	s_nop 0
	v_readfirstlane_b32 s23, v0
	s_mul_i32 s22, s22, s23
	s_mul_hi_u32 s22, s23, s22
	s_add_i32 s23, s23, s22
	s_mul_hi_u32 s22, s5, s23
	s_mul_i32 s23, s22, s20
	s_sub_i32 s5, s5, s23
	s_add_i32 s24, s22, 1
	s_sub_i32 s23, s5, s20
	s_cmp_ge_u32 s5, s20
	s_cselect_b32 s22, s24, s22
	s_cselect_b32 s5, s23, s5
	s_add_i32 s23, s22, 1
	s_cmp_ge_u32 s5, s20
	s_cselect_b32 s5, s23, s22
	s_xor_b32 s5, s5, s21
	s_sub_i32 s36, s5, s21
	s_mul_i32 s5, s36, s19
	s_sub_i32 s4, s4, s5
	s_add_i32 s4, s18, s4
	s_mov_b64 s[18:19], -1

;     __host__ __device__ bool next(int i, Unit& u) const { if (lo + i >= hi) return false; return base.next(lo + i, u); }
; __device__ __forceinline__ void flag_set(unsigned* f) {
;     asm volatile("s_waitcnt vmcnt(0)" ::: "memory");
;     __syncthreads();
;     if (threadIdx.x == 0) { __builtin_amdgcn_fence(__ATOMIC_RELEASE, "agent"); asm volatile("s_waitcnt vmcnt(0)" ::: "memory"); __hip_atomic_store(f, 1u, __ATOMIC_RELAXED, __HIP_MEMORY_SCOPE_AGENT); }
; }
; __global__ void __launch_bounds__(NWAVES * 64, 2) mega_fwd(Args a) {
;     ...
;             else { pg8::Unit u7; S.next(6, u7); flag_set(gflag + u7.pm); }
.LBB0_160:
	s_waitcnt vmcnt(0)
	s_waitcnt vmcnt(0)
	s_barrier
	s_and_saveexec_b64 s[18:19], s[0:1]
	s_cbranch_execz .LBB0_162
	s_ashr_i32 s17, s16, 31
	s_lshl_b64 s[20:21], s[16:17], 2
	buffer_wbl2 sc1
	s_waitcnt vmcnt(0)
	s_add_u32 s20, s76, s20
	s_addc_u32 s21, s77, s21
	global_atomic_add v155, v181, s[76:77] offset:260

; #define LAS __attribute__((address_space(3)))
; __global__ void __launch_bounds__(NWAVES * 64, 2) mega_fwd(Args a) {
;     ...
;         for (int rep_ = 0; rep_ < REP_P2B; ++rep_)
;         for (int i = 0;; ++i) {
;             int u;
;             if (tid == 0) *(volatile LAS unsigned*)((LAS unsigned char*)lds + QSLOT_OFF) = __hip_atomic_fetch_add(qctr, 1u, __ATOMIC_RELAXED, __HIP_MEMORY_SCOPE_AGENT);
;             __syncthreads();
;             u = __builtin_amdgcn_readfirstlane((int)*(volatile LAS unsigned*)((LAS unsigned char*)lds + QSLOT_OFF));
;             if (u >= 1024) break;
;             const int h = u >> 6, b = (u >> 5) & 1, qb = u & 31;
;             if (split7 && h >= 12) flag_wait(gflag + b * 32 + qb);
.LBB0_330:
	s_mov_b32 s90, 0
	v_readlane_b32 s76, v254, 61
	v_readlane_b32 s56, v254, 30
	v_readlane_b32 s77, v254, 62
	s_add_u32 s30, s76, 0x3000800
	v_readlane_b32 s0, v254, 28
	v_readlane_b32 s68, v254, 42
	v_readlane_b32 s69, v254, 43
	s_addc_u32 s33, s77, 0
	v_sub_u32_e32 v0, v232, v238
	s_add_i32 s34, 0, 0x23fc0
	v_readlane_b32 s1, v254, 29
	v_readlane_b32 s58, v254, 32
	v_readlane_b32 s59, v254, 33
	v_readlane_b32 s60, v254, 34
	v_readlane_b32 s61, v254, 35
	v_readlane_b32 s62, v254, 36
	v_readlane_b32 s63, v254, 37
	v_readlane_b32 s64, v254, 38
	v_readlane_b32 s65, v254, 39
	v_readlane_b32 s72, v254, 52
	v_readlane_b32 s68, v254, 56
	s_mov_b32 s7, 0
	v_cmp_eq_u32_e64 s[2:3], 0, v229
	v_readlane_b32 s78, v254, 63
	v_readlane_b32 s79, v255, 0
	v_lshlrev_b32_e32 v194, 8, v231
	v_add_u32_e32 v195, 0xfffffec5, v0
	v_mov_b32_e32 v1, 0
	v_mov_b32_e32 v196, s34
	s_xor_b64 s[8:9], s[0:1], -1
	s_movk_i32 s35, 0x80
	s_movk_i32 s36, 0xff7f
	s_mov_b32 s37, 0x41000000
	s_mov_b32 s38, 0x3fb8aa3b
	v_lshlrev_b32_e32 v197, 1, v228
	v_mov_b32_e32 v198, 0xff800000
	v_readlane_b32 s66, v254, 40
	v_readlane_b32 s67, v254, 41
	v_readlane_b32 s70, v254, 44
	v_readlane_b32 s71, v254, 45
	v_readlane_b32 s73, v254, 53
	v_readlane_b32 s58, v254, 46
	v_readlane_b32 s59, v254, 47
	v_readlane_b32 s60, v254, 22
	v_readlane_b32 s61, v254, 23
	v_readlane_b32 s62, v254, 24
	v_readlane_b32 s63, v254, 25
	v_readlane_b32 s64, v254, 26
	v_readlane_b32 s65, v254, 27
	v_readlane_b32 s69, v254, 57
	v_readlane_b32 s57, v254, 31
	s_branch .LBB0_334

; __device__ __forceinline__ void flag_wait(unsigned* f) {
;     if (threadIdx.x == 0) { while (__hip_atomic_load(f, __ATOMIC_RELAXED, __HIP_MEMORY_SCOPE_AGENT) == 0u) __builtin_amdgcn_s_sleep(2);
;         __builtin_amdgcn_fence(__ATOMIC_ACQUIRE, "agent"); asm volatile("s_waitcnt vmcnt(0)" ::: "memory"); }
;     __syncthreads();
; __global__ void __launch_bounds__(NWAVES * 64, 2) mega_fwd(Args a) {
;     ...
;             if (u >= 1024) break;
;             const int h = u >> 6, b = (u >> 5) & 1, qb = u & 31;
;             if (split7 && h >= 12) flag_wait(gflag + b * 32 + qb);
.LBB0_338:
	s_or_b64 exec, exec, s[0:1]
	s_waitcnt lgkmcnt(0)
	s_barrier
	ds_read_b32 v0, v196
	s_mov_b64 s[0:1], -1
	s_waitcnt lgkmcnt(0)
	v_readfirstlane_b32 s13, v0
	s_cmpk_gt_i32 s13, 0x3ff
	s_cbranch_scc1 .LBB0_333
	s_ashr_i32 s0, s13, 6
	s_bfe_u32 s6, s13, 0x10005
	s_and_b32 s12, s13, 31
	s_cmp_lt_i32 s0, 12
	s_cselect_b64 s[4:5], -1, 0
	s_mov_b64 s[4:5], s[8:9]
	s_and_b64 vcc, exec, s[4:5]
	s_cbranch_vccnz .LBB0_345
	s_cmp_lg_u32 s90, 0
	s_cbranch_scc1 .LBB0_345
	s_and_saveexec_b64 s[4:5], s[2:3]
	s_cbranch_execz .Lfw_join
.Lfw_loop:
	global_load_dword v241, v1, s[76:77] offset:260 sc1
	s_waitcnt vmcnt(0)
	v_cmp_gt_u32_e32 vcc, s83, v241
	s_cbranch_vccz .Lfw_done
	s_sleep 2
	s_branch .Lfw_loop

; __device__ __forceinline__ void flag_wait(unsigned* f) {
;     if (threadIdx.x == 0) { while (__hip_atomic_load(f, __ATOMIC_RELAXED, __HIP_MEMORY_SCOPE_AGENT) == 0u) __builtin_amdgcn_s_sleep(2);
;         __builtin_amdgcn_fence(__ATOMIC_ACQUIRE, "agent"); asm volatile("s_waitcnt vmcnt(0)" ::: "memory"); }
;     __syncthreads();
; }
.Lfw_join:
	s_or_b64 exec, exec, s[4:5]
	s_barrier
	s_mov_b32 s90, 1
